# prologue: w_branch and w_out transposes also through the software-pipelined tile loop
# speedup vs baseline: 1.0032x; 1.0008x over previous
; DEV void transpose_item(const float* __restrict__ src, int N, int K, u16* __restrict__ dst,
;                         const float* __restrict__ gain, int tn, int tk, char* smem, int tid) {
;   float* tile = (float*)smem;
;   __syncthreads();
; #pragma unroll
;   for (int i = 0; i < 2; ++i) {
;     int kk = (tid >> 4) + 32 * i, n4 = (tid & 15) * 4;
;     int k = tk * 64 + kk, n = tn * 64 + n4;
;     float4 v = make_float4(0.f, 0.f, 0.f, 0.f);
;     if (n < N) v = *(const float4*)(src + (long)k * N + n);
;     float gsc = gain ? gain[k] : 1.f;
;     tile[kk * 65 + n4 + 0] = v.x * gsc;
;     tile[kk * 65 + n4 + 1] = v.y * gsc;
;     tile[kk * 65 + n4 + 2] = v.z * gsc;
;     tile[kk * 65 + n4 + 3] = v.w * gsc;
;   }
;   __syncthreads();
.LBB0_5:
	s_or_b64 exec, exec, s[8:9]
	v_writelane_b32 v253, s2, 6
	s_cmpk_gt_i32 s2, 0x2e00
	s_cbranch_scc1 .LBB0_89
	v_readlane_b32 s0, v253, 0
	v_readlane_b32 s1, v253, 1
	s_load_dwordx16 s[12:27], s[0:1], 0xa0
	s_load_dwordx8 s[52:59], s[0:1], 0x38
	s_load_dwordx4 s[4:7], s[0:1], 0x80
	s_load_dwordx4 s[44:47], s[0:1], 0x58
	s_load_dwordx2 s[2:3], s[0:1], 0x8
	s_load_dwordx4 s[48:51], s[0:1], 0x18
	s_mov_b32 s43, 0
	v_mov_b32_e32 v11, 0
	s_waitcnt lgkmcnt(0)
	s_cmp_lg_u64 s[56:57], 0
	v_writelane_b32 v253, s4, 7
	s_cselect_b64 s[34:35], -1, 0
	s_cmp_lg_u64 s[54:55], 0
	v_writelane_b32 v253, s5, 8
	v_writelane_b32 v253, s6, 9
	v_writelane_b32 v253, s7, 10
	s_cselect_b64 s[38:39], -1, 0
	s_add_u32 s40, s50, 0x603000
	s_addc_u32 s41, s51, 0
	s_movk_i32 s68, 0x104
	v_cndmask_b32_e64 v1, 0, 1, s[34:35]
	s_movk_i32 s69, 0xc00
	v_cndmask_b32_e64 v46, 0, 1, s[38:39]
	s_mov_b32 s70, 0x8680
	s_movk_i32 s71, 0x3000
	s_mov_b32 s72, 0x3fb8aa3b
	s_mov_b32 s73, 0xc2ce8ed0
	s_mov_b32 s74, 0x42b17218
	s_movk_i32 s75, 0x1ff
	v_mov_b32_e32 v47, 0x3e91f4c4
	s_movk_i32 s76, 0x204
	s_mov_b32 s77, 0xfe5163ab
	s_mov_b32 s78, 0x3c439041
	s_mov_b32 s79, 0xdb629599
	s_mov_b32 s80, 0xf534ddc0
	s_mov_b32 s81, 0xfc2757d1
	s_mov_b32 s82, 0x4e441529
	s_mov_b32 s83, 0xa2f9836e
	s_mov_b32 s84, 0x3fc90fda
	s_mov_b32 s85, 0xbfc90fda
	v_mov_b32_e32 v48, 0x3c0881c4
	v_mov_b32_e32 v49, 0xbab64f3b
	s_brev_b32 s86, 1
	s_movk_i32 s87, 0x1f8
	s_movk_i32 s88, 0x4200
	s_mov_b32 s89, 0xbfb8aa3b
	s_mov_b32 s90, 0x42ce8ed0
	s_mov_b32 s91, 0xc2b17218
	s_movk_i32 s92, 0x3fff
	s_mov_b64 s[60:61], 0x6000
	s_movk_i32 s93, 0xd000
	s_movk_i32 s94, 0x2100
	s_movk_i32 s95, 0x840
	s_movk_i32 s96, 0x63f
	v_mov_b32_e32 v50, 0x7f800000
	v_mov_b32_e32 v51, 0x461c4000
	v_mov_b32_e32 v52, 0x37000000
	v_not_b32_e32 v53, 63
	v_not_b32_e32 v54, 31
	v_mov_b32_e32 v55, 0x7fc00000
	v_readlane_b32 s97, v253, 6
	v_and_b32_e32 v112, 15, v197
	v_lshlrev_b32_e32 v112, 2, v112
	v_lshrrev_b32_e32 v113, 4, v197
	v_mul_u32_u24_e32 v81, 0x41, v113
	v_add_u32_e32 v81, v81, v112
	v_lshlrev_b32_e32 v81, 2, v81
	v_lshrrev_b32_e32 v113, 3, v197
	v_and_b32_e32 v114, 7, v197
	v_lshlrev_b32_e32 v114, 3, v114
	v_mul_u32_u24_e32 v82, 0x41, v114
	v_add_u32_e32 v82, v82, v113
	v_lshlrev_b32_e32 v82, 2, v82
	v_lshrrev_b32_e32 v113, 4, v197
	v_mul_u32_u24_e32 v80, 0x8680, v113
	v_lshrrev_b32_e32 v113, 3, v197
	v_and_b32_e32 v114, 7, v197
	v_lshlrev_b32_e32 v114, 3, v114
	v_mul_u32_u24_e32 v83, 0x400, v113
	v_add_u32_e32 v83, v83, v114
	v_lshlrev_b32_e32 v83, 1, v83
	v_readlane_b32 s30, v253, 6
	s_lshr_b32 s0, s30, 7
	s_mul_i32 s0, s0, 241
	s_lshr_b32 s0, s0, 12
	s_mul_i32 s1, s0, 0x880
	s_sub_i32 s1, s30, s1
	s_and_b32 s42, s1, 15
	s_lshr_b32 s1, s1, 4
	s_min_u32 s1, s1, 134
	s_mul_i32 s9, s0, 0x21a0000
	s_mul_i32 s10, s42, 0x21a000
	s_add_u32 s9, s9, s10
	s_lshl_b32 s10, s1, 8
	s_add_u32 s9, s9, s10
	s_add_u32 s62, s52, s9
	s_addc_u32 s63, s53, 0
	s_add_u32 s64, s62, 0x10d000
	s_addc_u32 s65, s63, 0
	s_lshl_b32 s10, s1, 6
	s_sub_i32 s10, 0x219c, s10
	v_min_u32_e32 v121, s10, v112
	v_lshl_add_u32 v122, v121, 2, v80
	global_load_dwordx4 v[64:67], v122, s[62:63]
	global_load_dwordx4 v[68:71], v122, s[64:65]
	s_add_i32 s42, s30, 0x100
	s_lshr_b32 s0, s42, 7
	s_mul_i32 s0, s0, 241
	s_lshr_b32 s0, s0, 12
	s_mul_i32 s1, s0, 0x880
	s_sub_i32 s1, s42, s1
	s_and_b32 s42, s1, 15
	s_lshr_b32 s1, s1, 4
	s_min_u32 s1, s1, 134
	s_mul_i32 s9, s0, 0x21a0000
	s_mul_i32 s10, s42, 0x21a000
	s_add_u32 s9, s9, s10
	s_lshl_b32 s10, s1, 8
	s_add_u32 s9, s9, s10
	s_add_u32 s62, s52, s9
	s_addc_u32 s63, s53, 0
	s_add_u32 s64, s62, 0x10d000
	s_addc_u32 s65, s63, 0
	s_lshl_b32 s10, s1, 6
	s_sub_i32 s10, 0x219c, s10
	v_min_u32_e32 v121, s10, v112
	v_lshl_add_u32 v122, v121, 2, v80
	global_load_dwordx4 v[72:75], v122, s[62:63]
	global_load_dwordx4 v[76:79], v122, s[64:65]
	s_lshr_b32 s11, s30, 7
	s_mul_i32 s11, s11, 241
	s_lshr_b32 s11, s11, 12
	s_mul_i32 s31, s11, 0x880
	s_sub_i32 s31, s30, s31
	s_and_b32 s32, s31, 15
	s_lshr_b32 s31, s31, 4
	s_lshl_b32 s9, s31, 6
	s_sub_i32 s9, 0x21a0, s9
	v_cmp_gt_i32_e32 vcc, s9, v112
	s_waitcnt vmcnt(2)
	s_nop 1
	v_cndmask_b32_e32 v64, 0, v64, vcc
	v_cndmask_b32_e32 v65, 0, v65, vcc
	v_cndmask_b32_e32 v66, 0, v66, vcc
	v_cndmask_b32_e32 v67, 0, v67, vcc
	v_cndmask_b32_e32 v68, 0, v68, vcc
	v_cndmask_b32_e32 v69, 0, v69, vcc
	v_cndmask_b32_e32 v70, 0, v70, vcc
	v_cndmask_b32_e32 v71, 0, v71, vcc
	ds_write_b32 v81, v64 offset:0
	ds_write_b32 v81, v65 offset:4
	ds_write_b32 v81, v66 offset:8
	ds_write_b32 v81, v67 offset:12
	ds_write_b32 v81, v68 offset:8320
	ds_write_b32 v81, v69 offset:8324
	ds_write_b32 v81, v70 offset:8328
	ds_write_b32 v81, v71 offset:8332
	s_add_i32 s42, s30, 0x200
	s_cmpk_lt_u32 s42, 0x2200
	s_cselect_b32 s42, s42, s30
	s_lshr_b32 s0, s42, 7
	s_mul_i32 s0, s0, 241
	s_lshr_b32 s0, s0, 12
	s_mul_i32 s1, s0, 0x880
	s_sub_i32 s1, s42, s1
	s_and_b32 s42, s1, 15
	s_lshr_b32 s1, s1, 4
	s_min_u32 s1, s1, 134
	s_mul_i32 s9, s0, 0x21a0000
	s_mul_i32 s10, s42, 0x21a000
	s_add_u32 s9, s9, s10
	s_lshl_b32 s10, s1, 8
	s_add_u32 s9, s9, s10
	s_add_u32 s62, s52, s9
	s_addc_u32 s63, s53, 0
	s_add_u32 s64, s62, 0x10d000
	s_addc_u32 s65, s63, 0
	s_lshl_b32 s10, s1, 6
	s_sub_i32 s10, 0x219c, s10
	v_min_u32_e32 v121, s10, v112
	v_lshl_add_u32 v122, v121, 2, v80
	global_load_dwordx4 v[64:67], v122, s[62:63]
	global_load_dwordx4 v[68:71], v122, s[64:65]
	s_waitcnt lgkmcnt(0)
	s_barrier
; DEV void transpose_item(const float* __restrict__ src, int N, int K, u16* __restrict__ dst,
;                         const float* __restrict__ gain, int tn, int tk, char* smem, int tid) {
;   float* tile = (float*)smem;
;   __syncthreads();
; #pragma unroll
;   for (int i = 0; i < 2; ++i) {
;     int kk = (tid >> 4) + 32 * i, n4 = (tid & 15) * 4;
;     int k = tk * 64 + kk, n = tn * 64 + n4;
;     float4 v = make_float4(0.f, 0.f, 0.f, 0.f);
;     if (n < N) v = *(const float4*)(src + (long)k * N + n);
;     float gsc = gain ? gain[k] : 1.f;
;     tile[kk * 65 + n4 + 0] = v.x * gsc;
;     tile[kk * 65 + n4 + 1] = v.y * gsc;
;     tile[kk * 65 + n4 + 2] = v.z * gsc;
;     tile[kk * 65 + n4 + 3] = v.w * gsc;
;   }
;   __syncthreads();
;   int n = tid >> 3, kc = (tid & 7) * 8;
;   uint4 o;
;   o.x = pack2(tile[(kc + 0) * 65 + n], tile[(kc + 1) * 65 + n]);
;   o.y = pack2(tile[(kc + 2) * 65 + n], tile[(kc + 3) * 65 + n]);
;   o.z = pack2(tile[(kc + 4) * 65 + n], tile[(kc + 5) * 65 + n]);
;   o.w = pack2(tile[(kc + 6) * 65 + n], tile[(kc + 7) * 65 + n]);
;   *(uint4*)(dst + (long)(tn * 64 + n) * K + tk * 64 + kc) = o;
	ds_read_b32 v113, v82 offset:0
	ds_read_b32 v114, v82 offset:260
	ds_read_b32 v115, v82 offset:520
	ds_read_b32 v116, v82 offset:780
	ds_read_b32 v117, v82 offset:1040
	ds_read_b32 v118, v82 offset:1300
	ds_read_b32 v119, v82 offset:1560
	ds_read_b32 v120, v82 offset:1820
	s_mul_i32 s9, s11, 0x1100000
	s_mul_i32 s10, s31, 0x20000
	s_add_u32 s9, s9, s10
	s_lshl_b32 s10, s32, 7
	s_add_u32 s9, s9, s10
	s_add_u32 s66, s12, s9
	s_addc_u32 s67, s13, 0
	s_waitcnt lgkmcnt(0)
	v_cvt_pk_bf16_f32 v128, v113, v114
	v_cvt_pk_bf16_f32 v129, v115, v116
	v_cvt_pk_bf16_f32 v130, v117, v118
	v_cvt_pk_bf16_f32 v131, v119, v120
	global_store_dwordx4 v83, v[128:131], s[66:67]
	s_addk_i32 s30, 0x100
	s_lshr_b32 s11, s30, 7
	s_mul_i32 s11, s11, 241
	s_lshr_b32 s11, s11, 12
	s_mul_i32 s31, s11, 0x880
	s_sub_i32 s31, s30, s31
	s_and_b32 s32, s31, 15
	s_lshr_b32 s31, s31, 4
	s_lshl_b32 s9, s31, 6
	s_sub_i32 s9, 0x21a0, s9
	v_cmp_gt_i32_e32 vcc, s9, v112
	s_waitcnt vmcnt(3)
	s_nop 1
	v_cndmask_b32_e32 v72, 0, v72, vcc
	v_cndmask_b32_e32 v73, 0, v73, vcc
	v_cndmask_b32_e32 v74, 0, v74, vcc
	v_cndmask_b32_e32 v75, 0, v75, vcc
	v_cndmask_b32_e32 v76, 0, v76, vcc
	v_cndmask_b32_e32 v77, 0, v77, vcc
	v_cndmask_b32_e32 v78, 0, v78, vcc
	v_cndmask_b32_e32 v79, 0, v79, vcc
	ds_write_b32 v81, v72 offset:16640
	ds_write_b32 v81, v73 offset:16644
	ds_write_b32 v81, v74 offset:16648
	ds_write_b32 v81, v75 offset:16652
	ds_write_b32 v81, v76 offset:24960
	ds_write_b32 v81, v77 offset:24964
	ds_write_b32 v81, v78 offset:24968
	ds_write_b32 v81, v79 offset:24972
	s_add_i32 s42, s30, 0x200
	s_cmpk_lt_u32 s42, 0x2200
	s_cselect_b32 s42, s42, s30
	s_lshr_b32 s0, s42, 7
	s_mul_i32 s0, s0, 241
	s_lshr_b32 s0, s0, 12
	s_mul_i32 s1, s0, 0x880
	s_sub_i32 s1, s42, s1
	s_and_b32 s42, s1, 15
	s_lshr_b32 s1, s1, 4
	s_min_u32 s1, s1, 134
	s_mul_i32 s9, s0, 0x21a0000
	s_mul_i32 s10, s42, 0x21a000
	s_add_u32 s9, s9, s10
	s_lshl_b32 s10, s1, 8
	s_add_u32 s9, s9, s10
	s_add_u32 s62, s52, s9
	s_addc_u32 s63, s53, 0
	s_add_u32 s64, s62, 0x10d000
	s_addc_u32 s65, s63, 0
	s_lshl_b32 s10, s1, 6
	s_sub_i32 s10, 0x219c, s10
	v_min_u32_e32 v121, s10, v112
	v_lshl_add_u32 v122, v121, 2, v80
	global_load_dwordx4 v[72:75], v122, s[62:63]
	global_load_dwordx4 v[76:79], v122, s[64:65]
	s_waitcnt lgkmcnt(0)
	s_barrier
	ds_read_b32 v113, v82 offset:16640
	ds_read_b32 v114, v82 offset:16900
	ds_read_b32 v115, v82 offset:17160
	ds_read_b32 v116, v82 offset:17420
	ds_read_b32 v117, v82 offset:17680
	ds_read_b32 v118, v82 offset:17940
	ds_read_b32 v119, v82 offset:18200
	ds_read_b32 v120, v82 offset:18460
	s_mul_i32 s9, s11, 0x1100000
	s_mul_i32 s10, s31, 0x20000
	s_add_u32 s9, s9, s10
	s_lshl_b32 s10, s32, 7
	s_add_u32 s9, s9, s10
	s_add_u32 s66, s12, s9
	s_addc_u32 s67, s13, 0
	s_waitcnt lgkmcnt(0)
	v_cvt_pk_bf16_f32 v128, v113, v114
	v_cvt_pk_bf16_f32 v129, v115, v116
	v_cvt_pk_bf16_f32 v130, v117, v118
	v_cvt_pk_bf16_f32 v131, v119, v120
	global_store_dwordx4 v83, v[128:131], s[66:67]
	s_addk_i32 s30, 0x100
.Lpre_win_loop:
	s_lshr_b32 s11, s30, 7
	s_mul_i32 s11, s11, 241
	s_lshr_b32 s11, s11, 12
	s_mul_i32 s31, s11, 0x880
	s_sub_i32 s31, s30, s31
	s_and_b32 s32, s31, 15
	s_lshr_b32 s31, s31, 4
	s_lshl_b32 s9, s31, 6
	s_sub_i32 s9, 0x21a0, s9
	v_cmp_gt_i32_e32 vcc, s9, v112
	s_waitcnt vmcnt(4)
	s_nop 1
	v_cndmask_b32_e32 v64, 0, v64, vcc
	v_cndmask_b32_e32 v65, 0, v65, vcc
	v_cndmask_b32_e32 v66, 0, v66, vcc
	v_cndmask_b32_e32 v67, 0, v67, vcc
	v_cndmask_b32_e32 v68, 0, v68, vcc
	v_cndmask_b32_e32 v69, 0, v69, vcc
	v_cndmask_b32_e32 v70, 0, v70, vcc
	v_cndmask_b32_e32 v71, 0, v71, vcc
	ds_write_b32 v81, v64 offset:0
	ds_write_b32 v81, v65 offset:4
	ds_write_b32 v81, v66 offset:8
	ds_write_b32 v81, v67 offset:12
	ds_write_b32 v81, v68 offset:8320
	ds_write_b32 v81, v69 offset:8324
	ds_write_b32 v81, v70 offset:8328
	ds_write_b32 v81, v71 offset:8332
	s_add_i32 s42, s30, 0x200
	s_cmpk_lt_u32 s42, 0x2200
	s_cselect_b32 s42, s42, s30
	s_lshr_b32 s0, s42, 7
	s_mul_i32 s0, s0, 241
	s_lshr_b32 s0, s0, 12
	s_mul_i32 s1, s0, 0x880
	s_sub_i32 s1, s42, s1
	s_and_b32 s42, s1, 15
	s_lshr_b32 s1, s1, 4
	s_min_u32 s1, s1, 134
	s_mul_i32 s9, s0, 0x21a0000
	s_mul_i32 s10, s42, 0x21a000
	s_add_u32 s9, s9, s10
	s_lshl_b32 s10, s1, 8
	s_add_u32 s9, s9, s10
	s_add_u32 s62, s52, s9
	s_addc_u32 s63, s53, 0
	s_add_u32 s64, s62, 0x10d000
	s_addc_u32 s65, s63, 0
	s_lshl_b32 s10, s1, 6
	s_sub_i32 s10, 0x219c, s10
	v_min_u32_e32 v121, s10, v112
	v_lshl_add_u32 v122, v121, 2, v80
	global_load_dwordx4 v[64:67], v122, s[62:63]
	global_load_dwordx4 v[68:71], v122, s[64:65]
	s_waitcnt lgkmcnt(0)
	s_barrier
; DEV void transpose_item(const float* __restrict__ src, int N, int K, u16* __restrict__ dst,
;                         const float* __restrict__ gain, int tn, int tk, char* smem, int tid) {
;   float* tile = (float*)smem;
;   __syncthreads();
; #pragma unroll
;   for (int i = 0; i < 2; ++i) {
;     int kk = (tid >> 4) + 32 * i, n4 = (tid & 15) * 4;
;     int k = tk * 64 + kk, n = tn * 64 + n4;
;     float4 v = make_float4(0.f, 0.f, 0.f, 0.f);
;     if (n < N) v = *(const float4*)(src + (long)k * N + n);
;     float gsc = gain ? gain[k] : 1.f;
;     tile[kk * 65 + n4 + 0] = v.x * gsc;
;     tile[kk * 65 + n4 + 1] = v.y * gsc;
;     tile[kk * 65 + n4 + 2] = v.z * gsc;
;     tile[kk * 65 + n4 + 3] = v.w * gsc;
;   }
;   __syncthreads();
;   int n = tid >> 3, kc = (tid & 7) * 8;
;   uint4 o;
;   o.x = pack2(tile[(kc + 0) * 65 + n], tile[(kc + 1) * 65 + n]);
;   o.y = pack2(tile[(kc + 2) * 65 + n], tile[(kc + 3) * 65 + n]);
;   o.z = pack2(tile[(kc + 4) * 65 + n], tile[(kc + 5) * 65 + n]);
;   o.w = pack2(tile[(kc + 6) * 65 + n], tile[(kc + 7) * 65 + n]);
;   *(uint4*)(dst + (long)(tn * 64 + n) * K + tk * 64 + kc) = o;
; DEV void pre_item(const Params& p, int it, char* smem, int tid) {
;     ...
;   if (it < PRE_T_BR) {
;     int m = it / 128, r = it % 128;
;     transpose_item(p.w_branch + (long)m * 512 * 1024, 1024, 512, p.WbrT + (long)m * 1024 * 512, nullptr, r / 8, r % 8, smem, tid);
;     return;
	ds_read_b32 v113, v82 offset:0
	ds_read_b32 v114, v82 offset:260
	ds_read_b32 v115, v82 offset:520
	ds_read_b32 v116, v82 offset:780
	ds_read_b32 v117, v82 offset:1040
	ds_read_b32 v118, v82 offset:1300
	ds_read_b32 v119, v82 offset:1560
	ds_read_b32 v120, v82 offset:1820
	s_mul_i32 s9, s11, 0x1100000
	s_mul_i32 s10, s31, 0x20000
	s_add_u32 s9, s9, s10
	s_lshl_b32 s10, s32, 7
	s_add_u32 s9, s9, s10
	s_add_u32 s66, s12, s9
	s_addc_u32 s67, s13, 0
	s_waitcnt lgkmcnt(0)
	v_cvt_pk_bf16_f32 v128, v113, v114
	v_cvt_pk_bf16_f32 v129, v115, v116
	v_cvt_pk_bf16_f32 v130, v117, v118
	v_cvt_pk_bf16_f32 v131, v119, v120
	global_store_dwordx4 v83, v[128:131], s[66:67]
	s_addk_i32 s30, 0x100
	s_lshr_b32 s11, s30, 7
	s_mul_i32 s11, s11, 241
	s_lshr_b32 s11, s11, 12
	s_mul_i32 s31, s11, 0x880
	s_sub_i32 s31, s30, s31
	s_and_b32 s32, s31, 15
	s_lshr_b32 s31, s31, 4
	s_lshl_b32 s9, s31, 6
	s_sub_i32 s9, 0x21a0, s9
	v_cmp_gt_i32_e32 vcc, s9, v112
	s_waitcnt vmcnt(4)
	s_nop 1
	v_cndmask_b32_e32 v72, 0, v72, vcc
	v_cndmask_b32_e32 v73, 0, v73, vcc
	v_cndmask_b32_e32 v74, 0, v74, vcc
	v_cndmask_b32_e32 v75, 0, v75, vcc
	v_cndmask_b32_e32 v76, 0, v76, vcc
	v_cndmask_b32_e32 v77, 0, v77, vcc
	v_cndmask_b32_e32 v78, 0, v78, vcc
	v_cndmask_b32_e32 v79, 0, v79, vcc
	ds_write_b32 v81, v72 offset:16640
	ds_write_b32 v81, v73 offset:16644
	ds_write_b32 v81, v74 offset:16648
	ds_write_b32 v81, v75 offset:16652
	ds_write_b32 v81, v76 offset:24960
	ds_write_b32 v81, v77 offset:24964
	ds_write_b32 v81, v78 offset:24968
	ds_write_b32 v81, v79 offset:24972
	s_add_i32 s42, s30, 0x200
	s_cmpk_lt_u32 s42, 0x2200
	s_cselect_b32 s42, s42, s30
	s_lshr_b32 s0, s42, 7
	s_mul_i32 s0, s0, 241
	s_lshr_b32 s0, s0, 12
	s_mul_i32 s1, s0, 0x880
	s_sub_i32 s1, s42, s1
	s_and_b32 s42, s1, 15
	s_lshr_b32 s1, s1, 4
	s_min_u32 s1, s1, 134
	s_mul_i32 s9, s0, 0x21a0000
	s_mul_i32 s10, s42, 0x21a000
	s_add_u32 s9, s9, s10
	s_lshl_b32 s10, s1, 8
	s_add_u32 s9, s9, s10
	s_add_u32 s62, s52, s9
	s_addc_u32 s63, s53, 0
	s_add_u32 s64, s62, 0x10d000
	s_addc_u32 s65, s63, 0
	s_lshl_b32 s10, s1, 6
	s_sub_i32 s10, 0x219c, s10
	v_min_u32_e32 v121, s10, v112
	v_lshl_add_u32 v122, v121, 2, v80
	global_load_dwordx4 v[72:75], v122, s[62:63]
	global_load_dwordx4 v[76:79], v122, s[64:65]
	s_waitcnt lgkmcnt(0)
	s_barrier
	ds_read_b32 v113, v82 offset:16640
	ds_read_b32 v114, v82 offset:16900
	ds_read_b32 v115, v82 offset:17160
	ds_read_b32 v116, v82 offset:17420
	ds_read_b32 v117, v82 offset:17680
	ds_read_b32 v118, v82 offset:17940
	ds_read_b32 v119, v82 offset:18200
	ds_read_b32 v120, v82 offset:18460
	s_mul_i32 s9, s11, 0x1100000
	s_mul_i32 s10, s31, 0x20000
	s_add_u32 s9, s9, s10
	s_lshl_b32 s10, s32, 7
	s_add_u32 s9, s9, s10
	s_add_u32 s66, s12, s9
	s_addc_u32 s67, s13, 0
	s_waitcnt lgkmcnt(0)
	v_cvt_pk_bf16_f32 v128, v113, v114
	v_cvt_pk_bf16_f32 v129, v115, v116
	v_cvt_pk_bf16_f32 v130, v117, v118
	v_cvt_pk_bf16_f32 v131, v119, v120
	global_store_dwordx4 v83, v[128:131], s[66:67]
	s_addk_i32 s30, 0x100
	s_cmpk_lt_u32 s30, 0x2200
	s_cbranch_scc1 .Lpre_win_loop
	s_waitcnt vmcnt(0)
	s_barrier
	v_lshrrev_b32_e32 v113, 4, v197
	v_mul_u32_u24_e32 v80, 0x1000, v113
	v_lshrrev_b32_e32 v113, 3, v197
	v_and_b32_e32 v114, 7, v197
	v_lshlrev_b32_e32 v114, 3, v114
	v_mul_u32_u24_e32 v83, 0x200, v113
	v_add_u32_e32 v83, v83, v114
	v_lshlrev_b32_e32 v83, 1, v83
	v_readlane_b32 s30, v253, 6
	s_lshr_b32 s0, s30, 7
	s_and_b32 s1, s30, 127
	s_and_b32 s42, s1, 7
	s_lshr_b32 s1, s1, 3
	s_mul_i32 s9, s0, 0x200000
	s_mul_i32 s10, s42, 0x40000
	s_add_u32 s9, s9, s10
	s_lshl_b32 s10, s1, 8
	s_add_u32 s9, s9, s10
	s_add_u32 s62, s4, s9
	s_addc_u32 s63, s5, 0
	s_add_u32 s64, s62, 0x20000
	s_addc_u32 s65, s63, 0
	v_lshl_add_u32 v122, v112, 2, v80
	global_load_dwordx4 v[64:67], v122, s[62:63]
	global_load_dwordx4 v[68:71], v122, s[64:65]
	s_add_i32 s42, s30, 0x100
	s_lshr_b32 s0, s42, 7
	s_and_b32 s1, s42, 127
	s_and_b32 s42, s1, 7
	s_lshr_b32 s1, s1, 3
	s_mul_i32 s9, s0, 0x200000
	s_mul_i32 s10, s42, 0x40000
	s_add_u32 s9, s9, s10
	s_lshl_b32 s10, s1, 8
	s_add_u32 s9, s9, s10
	s_add_u32 s62, s4, s9
	s_addc_u32 s63, s5, 0
	s_add_u32 s64, s62, 0x20000
	s_addc_u32 s65, s63, 0
	v_lshl_add_u32 v122, v112, 2, v80
	global_load_dwordx4 v[72:75], v122, s[62:63]
	global_load_dwordx4 v[76:79], v122, s[64:65]
	s_lshr_b32 s11, s30, 7
	s_and_b32 s31, s30, 127
	s_and_b32 s32, s31, 7
	s_lshr_b32 s31, s31, 3
	s_waitcnt vmcnt(2)
	ds_write_b32 v81, v64 offset:0
	ds_write_b32 v81, v65 offset:4
	ds_write_b32 v81, v66 offset:8
	ds_write_b32 v81, v67 offset:12
	ds_write_b32 v81, v68 offset:8320
	ds_write_b32 v81, v69 offset:8324
	ds_write_b32 v81, v70 offset:8328
	ds_write_b32 v81, v71 offset:8332
	s_add_i32 s42, s30, 0x200
	s_cmpk_lt_u32 s42, 0x600
	s_cselect_b32 s42, s42, s30
	s_lshr_b32 s0, s42, 7
	s_and_b32 s1, s42, 127
	s_and_b32 s42, s1, 7
	s_lshr_b32 s1, s1, 3
	s_mul_i32 s9, s0, 0x200000
	s_mul_i32 s10, s42, 0x40000
	s_add_u32 s9, s9, s10
	s_lshl_b32 s10, s1, 8
	s_add_u32 s9, s9, s10
	s_add_u32 s62, s4, s9
	s_addc_u32 s63, s5, 0
	s_add_u32 s64, s62, 0x20000
	s_addc_u32 s65, s63, 0
	v_lshl_add_u32 v122, v112, 2, v80
	global_load_dwordx4 v[64:67], v122, s[62:63]
	global_load_dwordx4 v[68:71], v122, s[64:65]
	s_waitcnt lgkmcnt(0)
	s_barrier
; DEV void transpose_item(const float* __restrict__ src, int N, int K, u16* __restrict__ dst,
;                         const float* __restrict__ gain, int tn, int tk, char* smem, int tid) {
;   float* tile = (float*)smem;
;   __syncthreads();
; #pragma unroll
;   for (int i = 0; i < 2; ++i) {
;     int kk = (tid >> 4) + 32 * i, n4 = (tid & 15) * 4;
;     int k = tk * 64 + kk, n = tn * 64 + n4;
;     float4 v = make_float4(0.f, 0.f, 0.f, 0.f);
;     if (n < N) v = *(const float4*)(src + (long)k * N + n);
;     float gsc = gain ? gain[k] : 1.f;
;     tile[kk * 65 + n4 + 0] = v.x * gsc;
;     tile[kk * 65 + n4 + 1] = v.y * gsc;
;     tile[kk * 65 + n4 + 2] = v.z * gsc;
;     tile[kk * 65 + n4 + 3] = v.w * gsc;
;   }
;   __syncthreads();
;   int n = tid >> 3, kc = (tid & 7) * 8;
;   uint4 o;
;   o.x = pack2(tile[(kc + 0) * 65 + n], tile[(kc + 1) * 65 + n]);
;   o.y = pack2(tile[(kc + 2) * 65 + n], tile[(kc + 3) * 65 + n]);
;   o.z = pack2(tile[(kc + 4) * 65 + n], tile[(kc + 5) * 65 + n]);
;   o.w = pack2(tile[(kc + 6) * 65 + n], tile[(kc + 7) * 65 + n]);
;   *(uint4*)(dst + (long)(tn * 64 + n) * K + tk * 64 + kc) = o;
; DEV void pre_item(const Params& p, int it, char* smem, int tid) {
;     ...
;   if (it < PRE_T_BR) {
;     int m = it / 128, r = it % 128;
;     transpose_item(p.w_branch + (long)m * 512 * 1024, 1024, 512, p.WbrT + (long)m * 1024 * 512, nullptr, r / 8, r % 8, smem, tid);
;     return;
	ds_read_b32 v113, v82 offset:0
	ds_read_b32 v114, v82 offset:260
	ds_read_b32 v115, v82 offset:520
	ds_read_b32 v116, v82 offset:780
	ds_read_b32 v117, v82 offset:1040
	ds_read_b32 v118, v82 offset:1300
	ds_read_b32 v119, v82 offset:1560
	ds_read_b32 v120, v82 offset:1820
	s_mul_i32 s9, s11, 0x100000
	s_mul_i32 s10, s31, 0x10000
	s_add_u32 s9, s9, s10
	s_lshl_b32 s10, s32, 7
	s_add_u32 s9, s9, s10
	s_add_u32 s66, s18, s9
	s_addc_u32 s67, s19, 0
	s_waitcnt lgkmcnt(0)
	v_cvt_pk_bf16_f32 v128, v113, v114
	v_cvt_pk_bf16_f32 v129, v115, v116
	v_cvt_pk_bf16_f32 v130, v117, v118
	v_cvt_pk_bf16_f32 v131, v119, v120
	global_store_dwordx4 v83, v[128:131], s[66:67]
	s_addk_i32 s30, 0x100
	s_lshr_b32 s11, s30, 7
	s_and_b32 s31, s30, 127
	s_and_b32 s32, s31, 7
	s_lshr_b32 s31, s31, 3
	s_waitcnt vmcnt(3)
	ds_write_b32 v81, v72 offset:16640
	ds_write_b32 v81, v73 offset:16644
	ds_write_b32 v81, v74 offset:16648
	ds_write_b32 v81, v75 offset:16652
	ds_write_b32 v81, v76 offset:24960
	ds_write_b32 v81, v77 offset:24964
	ds_write_b32 v81, v78 offset:24968
	ds_write_b32 v81, v79 offset:24972
	s_add_i32 s42, s30, 0x200
	s_cmpk_lt_u32 s42, 0x600
	s_cselect_b32 s42, s42, s30
	s_lshr_b32 s0, s42, 7
	s_and_b32 s1, s42, 127
	s_and_b32 s42, s1, 7
	s_lshr_b32 s1, s1, 3
	s_mul_i32 s9, s0, 0x200000
	s_mul_i32 s10, s42, 0x40000
	s_add_u32 s9, s9, s10
	s_lshl_b32 s10, s1, 8
	s_add_u32 s9, s9, s10
	s_add_u32 s62, s4, s9
	s_addc_u32 s63, s5, 0
	s_add_u32 s64, s62, 0x20000
	s_addc_u32 s65, s63, 0
	v_lshl_add_u32 v122, v112, 2, v80
	global_load_dwordx4 v[72:75], v122, s[62:63]
	global_load_dwordx4 v[76:79], v122, s[64:65]
	s_waitcnt lgkmcnt(0)
	s_barrier
	ds_read_b32 v113, v82 offset:16640
	ds_read_b32 v114, v82 offset:16900
	ds_read_b32 v115, v82 offset:17160
	ds_read_b32 v116, v82 offset:17420
	ds_read_b32 v117, v82 offset:17680
	ds_read_b32 v118, v82 offset:17940
	ds_read_b32 v119, v82 offset:18200
	ds_read_b32 v120, v82 offset:18460
	s_mul_i32 s9, s11, 0x100000
	s_mul_i32 s10, s31, 0x10000
	s_add_u32 s9, s9, s10
	s_lshl_b32 s10, s32, 7
	s_add_u32 s9, s9, s10
	s_add_u32 s66, s18, s9
	s_addc_u32 s67, s19, 0
	s_waitcnt lgkmcnt(0)
	v_cvt_pk_bf16_f32 v128, v113, v114
	v_cvt_pk_bf16_f32 v129, v115, v116
	v_cvt_pk_bf16_f32 v130, v117, v118
	v_cvt_pk_bf16_f32 v131, v119, v120
	global_store_dwordx4 v83, v[128:131], s[66:67]
	s_addk_i32 s30, 0x100
.Lpre_wbr_loop:
	s_lshr_b32 s11, s30, 7
	s_and_b32 s31, s30, 127
	s_and_b32 s32, s31, 7
	s_lshr_b32 s31, s31, 3
	s_waitcnt vmcnt(4)
	ds_write_b32 v81, v64 offset:0
	ds_write_b32 v81, v65 offset:4
	ds_write_b32 v81, v66 offset:8
	ds_write_b32 v81, v67 offset:12
	ds_write_b32 v81, v68 offset:8320
	ds_write_b32 v81, v69 offset:8324
	ds_write_b32 v81, v70 offset:8328
	ds_write_b32 v81, v71 offset:8332
	s_add_i32 s42, s30, 0x200
	s_cmpk_lt_u32 s42, 0x600
	s_cselect_b32 s42, s42, s30
	s_lshr_b32 s0, s42, 7
	s_and_b32 s1, s42, 127
	s_and_b32 s42, s1, 7
	s_lshr_b32 s1, s1, 3
	s_mul_i32 s9, s0, 0x200000
	s_mul_i32 s10, s42, 0x40000
	s_add_u32 s9, s9, s10
	s_lshl_b32 s10, s1, 8
	s_add_u32 s9, s9, s10
	s_add_u32 s62, s4, s9
	s_addc_u32 s63, s5, 0
	s_add_u32 s64, s62, 0x20000
	s_addc_u32 s65, s63, 0
	v_lshl_add_u32 v122, v112, 2, v80
	global_load_dwordx4 v[64:67], v122, s[62:63]
	global_load_dwordx4 v[68:71], v122, s[64:65]
	s_waitcnt lgkmcnt(0)
	s_barrier
	ds_read_b32 v113, v82 offset:0
	ds_read_b32 v114, v82 offset:260
	ds_read_b32 v115, v82 offset:520
	ds_read_b32 v116, v82 offset:780
	ds_read_b32 v117, v82 offset:1040
	ds_read_b32 v118, v82 offset:1300
	ds_read_b32 v119, v82 offset:1560
	ds_read_b32 v120, v82 offset:1820
	s_mul_i32 s9, s11, 0x100000
	s_mul_i32 s10, s31, 0x10000
	s_add_u32 s9, s9, s10
	s_lshl_b32 s10, s32, 7
	s_add_u32 s9, s9, s10
	s_add_u32 s66, s18, s9
	s_addc_u32 s67, s19, 0
	s_waitcnt lgkmcnt(0)
	v_cvt_pk_bf16_f32 v128, v113, v114
	v_cvt_pk_bf16_f32 v129, v115, v116
	v_cvt_pk_bf16_f32 v130, v117, v118
	v_cvt_pk_bf16_f32 v131, v119, v120
	global_store_dwordx4 v83, v[128:131], s[66:67]
	s_addk_i32 s30, 0x100
	s_lshr_b32 s11, s30, 7
	s_and_b32 s31, s30, 127
	s_and_b32 s32, s31, 7
	s_lshr_b32 s31, s31, 3
	s_waitcnt vmcnt(4)
	ds_write_b32 v81, v72 offset:16640
	ds_write_b32 v81, v73 offset:16644
	ds_write_b32 v81, v74 offset:16648
	ds_write_b32 v81, v75 offset:16652
	ds_write_b32 v81, v76 offset:24960
	ds_write_b32 v81, v77 offset:24964
	ds_write_b32 v81, v78 offset:24968
	ds_write_b32 v81, v79 offset:24972
	s_add_i32 s42, s30, 0x200
	s_cmpk_lt_u32 s42, 0x600
	s_cselect_b32 s42, s42, s30
	s_lshr_b32 s0, s42, 7
	s_and_b32 s1, s42, 127
	s_and_b32 s42, s1, 7
	s_lshr_b32 s1, s1, 3
	s_mul_i32 s9, s0, 0x200000
	s_mul_i32 s10, s42, 0x40000
	s_add_u32 s9, s9, s10
	s_lshl_b32 s10, s1, 8
	s_add_u32 s9, s9, s10
	s_add_u32 s62, s4, s9
	s_addc_u32 s63, s5, 0
	s_add_u32 s64, s62, 0x20000
	s_addc_u32 s65, s63, 0
	v_lshl_add_u32 v122, v112, 2, v80
	global_load_dwordx4 v[72:75], v122, s[62:63]
	global_load_dwordx4 v[76:79], v122, s[64:65]
	s_waitcnt lgkmcnt(0)
	s_barrier
	ds_read_b32 v113, v82 offset:16640
	ds_read_b32 v114, v82 offset:16900
	ds_read_b32 v115, v82 offset:17160
	ds_read_b32 v116, v82 offset:17420
	ds_read_b32 v117, v82 offset:17680
	ds_read_b32 v118, v82 offset:17940
	ds_read_b32 v119, v82 offset:18200
	ds_read_b32 v120, v82 offset:18460
	s_mul_i32 s9, s11, 0x100000
	s_mul_i32 s10, s31, 0x10000
	s_add_u32 s9, s9, s10
	s_lshl_b32 s10, s32, 7
	s_add_u32 s9, s9, s10
	s_add_u32 s66, s18, s9
	s_addc_u32 s67, s19, 0
	s_waitcnt lgkmcnt(0)
	v_cvt_pk_bf16_f32 v128, v113, v114
	v_cvt_pk_bf16_f32 v129, v115, v116
	v_cvt_pk_bf16_f32 v130, v117, v118
	v_cvt_pk_bf16_f32 v131, v119, v120
	global_store_dwordx4 v83, v[128:131], s[66:67]
	s_addk_i32 s30, 0x100
	s_cmpk_lt_u32 s30, 0x600
	s_cbranch_scc1 .Lpre_wbr_loop
; DEV void transpose_item(const float* __restrict__ src, int N, int K, u16* __restrict__ dst,
;                         const float* __restrict__ gain, int tn, int tk, char* smem, int tid) {
;   float* tile = (float*)smem;
;   __syncthreads();
; #pragma unroll
;   for (int i = 0; i < 2; ++i) {
;     int kk = (tid >> 4) + 32 * i, n4 = (tid & 15) * 4;
;     int k = tk * 64 + kk, n = tn * 64 + n4;
;     float4 v = make_float4(0.f, 0.f, 0.f, 0.f);
;     if (n < N) v = *(const float4*)(src + (long)k * N + n);
;     float gsc = gain ? gain[k] : 1.f;
;     tile[kk * 65 + n4 + 0] = v.x * gsc;
;     tile[kk * 65 + n4 + 1] = v.y * gsc;
;     tile[kk * 65 + n4 + 2] = v.z * gsc;
;     tile[kk * 65 + n4 + 3] = v.w * gsc;
;   }
;   __syncthreads();
;   int n = tid >> 3, kc = (tid & 7) * 8;
;   uint4 o;
;   o.x = pack2(tile[(kc + 0) * 65 + n], tile[(kc + 1) * 65 + n]);
;   o.y = pack2(tile[(kc + 2) * 65 + n], tile[(kc + 3) * 65 + n]);
;   o.z = pack2(tile[(kc + 4) * 65 + n], tile[(kc + 5) * 65 + n]);
;   o.w = pack2(tile[(kc + 6) * 65 + n], tile[(kc + 7) * 65 + n]);
;   *(uint4*)(dst + (long)(tn * 64 + n) * K + tk * 64 + kc) = o;
; DEV void pre_item(const Params& p, int it, char* smem, int tid) {
;     ...
;   {
;     int l = it / 256, r = it % 256;
;     transpose_item(p.w_out + (long)l * 1024 * 1024, 1024, 1024, p.WoutT + (long)l * 1024 * 1024, nullptr, r / 16, r % 16, smem, tid);
	s_waitcnt vmcnt(0)
	s_barrier
	v_lshrrev_b32_e32 v113, 4, v197
	v_mul_u32_u24_e32 v80, 0x1000, v113
	v_lshrrev_b32_e32 v113, 3, v197
	v_and_b32_e32 v114, 7, v197
	v_lshlrev_b32_e32 v114, 3, v114
	v_mul_u32_u24_e32 v83, 0x400, v113
	v_add_u32_e32 v83, v83, v114
	v_lshlrev_b32_e32 v83, 1, v83
	v_readlane_b32 s30, v253, 6
	s_lshr_b32 s0, s30, 8
	s_and_b32 s1, s30, 255
	s_and_b32 s42, s1, 15
	s_lshr_b32 s1, s1, 4
	s_mul_i32 s9, s0, 0x400000
	s_mul_i32 s10, s42, 0x40000
	s_add_u32 s9, s9, s10
	s_lshl_b32 s10, s1, 8
	s_add_u32 s9, s9, s10
	s_add_u32 s62, s6, s9
	s_addc_u32 s63, s7, 0
	s_add_u32 s64, s62, 0x20000
	s_addc_u32 s65, s63, 0
	v_lshl_add_u32 v122, v112, 2, v80
	global_load_dwordx4 v[64:67], v122, s[62:63]
	global_load_dwordx4 v[68:71], v122, s[64:65]
	s_add_i32 s42, s30, 0x100
	s_lshr_b32 s0, s42, 8
	s_and_b32 s1, s42, 255
	s_and_b32 s42, s1, 15
	s_lshr_b32 s1, s1, 4
	s_mul_i32 s9, s0, 0x400000
	s_mul_i32 s10, s42, 0x40000
	s_add_u32 s9, s9, s10
	s_lshl_b32 s10, s1, 8
	s_add_u32 s9, s9, s10
	s_add_u32 s62, s6, s9
	s_addc_u32 s63, s7, 0
	s_add_u32 s64, s62, 0x20000
	s_addc_u32 s65, s63, 0
	v_lshl_add_u32 v122, v112, 2, v80
	global_load_dwordx4 v[72:75], v122, s[62:63]
	global_load_dwordx4 v[76:79], v122, s[64:65]
	s_lshr_b32 s11, s30, 8
	s_and_b32 s31, s30, 255
	s_and_b32 s32, s31, 15
	s_lshr_b32 s31, s31, 4
	s_waitcnt vmcnt(2)
	ds_write_b32 v81, v64 offset:0
	ds_write_b32 v81, v65 offset:4
	ds_write_b32 v81, v66 offset:8
	ds_write_b32 v81, v67 offset:12
	ds_write_b32 v81, v68 offset:8320
	ds_write_b32 v81, v69 offset:8324
	ds_write_b32 v81, v70 offset:8328
	ds_write_b32 v81, v71 offset:8332
	s_add_i32 s42, s30, 0x200
	s_cmpk_lt_u32 s42, 0x400
	s_cselect_b32 s42, s42, s30
	s_lshr_b32 s0, s42, 8
	s_and_b32 s1, s42, 255
	s_and_b32 s42, s1, 15
	s_lshr_b32 s1, s1, 4
	s_mul_i32 s9, s0, 0x400000
	s_mul_i32 s10, s42, 0x40000
	s_add_u32 s9, s9, s10
	s_lshl_b32 s10, s1, 8
	s_add_u32 s9, s9, s10
	s_add_u32 s62, s6, s9
	s_addc_u32 s63, s7, 0
	s_add_u32 s64, s62, 0x20000
	s_addc_u32 s65, s63, 0
	v_lshl_add_u32 v122, v112, 2, v80
	global_load_dwordx4 v[64:67], v122, s[62:63]
	global_load_dwordx4 v[68:71], v122, s[64:65]
	s_waitcnt lgkmcnt(0)
	s_barrier
	ds_read_b32 v113, v82 offset:0
	ds_read_b32 v114, v82 offset:260
	ds_read_b32 v115, v82 offset:520
	ds_read_b32 v116, v82 offset:780
	ds_read_b32 v117, v82 offset:1040
	ds_read_b32 v118, v82 offset:1300
	ds_read_b32 v119, v82 offset:1560
	ds_read_b32 v120, v82 offset:1820
	s_mul_i32 s9, s11, 0x200000
	s_mul_i32 s10, s31, 0x20000
	s_add_u32 s9, s9, s10
	s_lshl_b32 s10, s32, 7
	s_add_u32 s9, s9, s10
	s_add_u32 s66, s20, s9
	s_addc_u32 s67, s21, 0
	s_waitcnt lgkmcnt(0)
	v_cvt_pk_bf16_f32 v128, v113, v114
	v_cvt_pk_bf16_f32 v129, v115, v116
	v_cvt_pk_bf16_f32 v130, v117, v118
	v_cvt_pk_bf16_f32 v131, v119, v120
	global_store_dwordx4 v83, v[128:131], s[66:67]
	s_addk_i32 s30, 0x100
	s_lshr_b32 s11, s30, 8
	s_and_b32 s31, s30, 255
	s_and_b32 s32, s31, 15
	s_lshr_b32 s31, s31, 4
	s_waitcnt vmcnt(3)
	ds_write_b32 v81, v72 offset:16640
	ds_write_b32 v81, v73 offset:16644
	ds_write_b32 v81, v74 offset:16648
	ds_write_b32 v81, v75 offset:16652
	ds_write_b32 v81, v76 offset:24960
	ds_write_b32 v81, v77 offset:24964
	ds_write_b32 v81, v78 offset:24968
	ds_write_b32 v81, v79 offset:24972
	s_add_i32 s42, s30, 0x200
	s_cmpk_lt_u32 s42, 0x400
	s_cselect_b32 s42, s42, s30
	s_lshr_b32 s0, s42, 8
	s_and_b32 s1, s42, 255
	s_and_b32 s42, s1, 15
	s_lshr_b32 s1, s1, 4
	s_mul_i32 s9, s0, 0x400000
	s_mul_i32 s10, s42, 0x40000
	s_add_u32 s9, s9, s10
	s_lshl_b32 s10, s1, 8
	s_add_u32 s9, s9, s10
	s_add_u32 s62, s6, s9
	s_addc_u32 s63, s7, 0
	s_add_u32 s64, s62, 0x20000
	s_addc_u32 s65, s63, 0
	v_lshl_add_u32 v122, v112, 2, v80
	global_load_dwordx4 v[72:75], v122, s[62:63]
	global_load_dwordx4 v[76:79], v122, s[64:65]
	s_waitcnt lgkmcnt(0)
	s_barrier
	ds_read_b32 v113, v82 offset:16640
	ds_read_b32 v114, v82 offset:16900
	ds_read_b32 v115, v82 offset:17160
	ds_read_b32 v116, v82 offset:17420
	ds_read_b32 v117, v82 offset:17680
	ds_read_b32 v118, v82 offset:17940
	ds_read_b32 v119, v82 offset:18200
	ds_read_b32 v120, v82 offset:18460
	s_mul_i32 s9, s11, 0x200000
	s_mul_i32 s10, s31, 0x20000
	s_add_u32 s9, s9, s10
	s_lshl_b32 s10, s32, 7
	s_add_u32 s9, s9, s10
	s_add_u32 s66, s20, s9
	s_addc_u32 s67, s21, 0
	s_waitcnt lgkmcnt(0)
	v_cvt_pk_bf16_f32 v128, v113, v114
	v_cvt_pk_bf16_f32 v129, v115, v116
	v_cvt_pk_bf16_f32 v130, v117, v118
	v_cvt_pk_bf16_f32 v131, v119, v120
	global_store_dwordx4 v83, v[128:131], s[66:67]
	s_addk_i32 s30, 0x100
; DEV void transpose_item(const float* __restrict__ src, int N, int K, u16* __restrict__ dst,
;                         const float* __restrict__ gain, int tn, int tk, char* smem, int tid) {
;   float* tile = (float*)smem;
;   __syncthreads();
; #pragma unroll
;   for (int i = 0; i < 2; ++i) {
;     int kk = (tid >> 4) + 32 * i, n4 = (tid & 15) * 4;
;     int k = tk * 64 + kk, n = tn * 64 + n4;
;     float4 v = make_float4(0.f, 0.f, 0.f, 0.f);
;     if (n < N) v = *(const float4*)(src + (long)k * N + n);
;     float gsc = gain ? gain[k] : 1.f;
;     tile[kk * 65 + n4 + 0] = v.x * gsc;
;     tile[kk * 65 + n4 + 1] = v.y * gsc;
;     tile[kk * 65 + n4 + 2] = v.z * gsc;
;     tile[kk * 65 + n4 + 3] = v.w * gsc;
;   }
;   __syncthreads();
;   int n = tid >> 3, kc = (tid & 7) * 8;
;   uint4 o;
;   o.x = pack2(tile[(kc + 0) * 65 + n], tile[(kc + 1) * 65 + n]);
;   o.y = pack2(tile[(kc + 2) * 65 + n], tile[(kc + 3) * 65 + n]);
;   o.z = pack2(tile[(kc + 4) * 65 + n], tile[(kc + 5) * 65 + n]);
;   o.w = pack2(tile[(kc + 6) * 65 + n], tile[(kc + 7) * 65 + n]);
;   *(uint4*)(dst + (long)(tn * 64 + n) * K + tk * 64 + kc) = o;
; DEV void pre_item(const Params& p, int it, char* smem, int tid) {
;     ...
;   {
;     int l = it / 256, r = it % 256;
;     transpose_item(p.w_out + (long)l * 1024 * 1024, 1024, 1024, p.WoutT + (long)l * 1024 * 1024, nullptr, r / 16, r % 16, smem, tid);
.Lpre_wout_loop:
	s_lshr_b32 s11, s30, 8
	s_and_b32 s31, s30, 255
	s_and_b32 s32, s31, 15
	s_lshr_b32 s31, s31, 4
	s_waitcnt vmcnt(4)
	ds_write_b32 v81, v64 offset:0
	ds_write_b32 v81, v65 offset:4
	ds_write_b32 v81, v66 offset:8
	ds_write_b32 v81, v67 offset:12
	ds_write_b32 v81, v68 offset:8320
	ds_write_b32 v81, v69 offset:8324
	ds_write_b32 v81, v70 offset:8328
	ds_write_b32 v81, v71 offset:8332
	s_add_i32 s42, s30, 0x200
	s_cmpk_lt_u32 s42, 0x400
	s_cselect_b32 s42, s42, s30
	s_lshr_b32 s0, s42, 8
	s_and_b32 s1, s42, 255
	s_and_b32 s42, s1, 15
	s_lshr_b32 s1, s1, 4
	s_mul_i32 s9, s0, 0x400000
	s_mul_i32 s10, s42, 0x40000
	s_add_u32 s9, s9, s10
	s_lshl_b32 s10, s1, 8
	s_add_u32 s9, s9, s10
	s_add_u32 s62, s6, s9
	s_addc_u32 s63, s7, 0
	s_add_u32 s64, s62, 0x20000
	s_addc_u32 s65, s63, 0
	v_lshl_add_u32 v122, v112, 2, v80
	global_load_dwordx4 v[64:67], v122, s[62:63]
	global_load_dwordx4 v[68:71], v122, s[64:65]
	s_waitcnt lgkmcnt(0)
	s_barrier
	ds_read_b32 v113, v82 offset:0
	ds_read_b32 v114, v82 offset:260
	ds_read_b32 v115, v82 offset:520
	ds_read_b32 v116, v82 offset:780
	ds_read_b32 v117, v82 offset:1040
	ds_read_b32 v118, v82 offset:1300
	ds_read_b32 v119, v82 offset:1560
	ds_read_b32 v120, v82 offset:1820
	s_mul_i32 s9, s11, 0x200000
	s_mul_i32 s10, s31, 0x20000
	s_add_u32 s9, s9, s10
	s_lshl_b32 s10, s32, 7
	s_add_u32 s9, s9, s10
	s_add_u32 s66, s20, s9
	s_addc_u32 s67, s21, 0
	s_waitcnt lgkmcnt(0)
	v_cvt_pk_bf16_f32 v128, v113, v114
	v_cvt_pk_bf16_f32 v129, v115, v116
	v_cvt_pk_bf16_f32 v130, v117, v118
	v_cvt_pk_bf16_f32 v131, v119, v120
	global_store_dwordx4 v83, v[128:131], s[66:67]
	s_addk_i32 s30, 0x100
	s_lshr_b32 s11, s30, 8
	s_and_b32 s31, s30, 255
	s_and_b32 s32, s31, 15
	s_lshr_b32 s31, s31, 4
	s_waitcnt vmcnt(4)
	ds_write_b32 v81, v72 offset:16640
	ds_write_b32 v81, v73 offset:16644
	ds_write_b32 v81, v74 offset:16648
	ds_write_b32 v81, v75 offset:16652
	ds_write_b32 v81, v76 offset:24960
	ds_write_b32 v81, v77 offset:24964
	ds_write_b32 v81, v78 offset:24968
	ds_write_b32 v81, v79 offset:24972
	s_add_i32 s42, s30, 0x200
	s_cmpk_lt_u32 s42, 0x400
	s_cselect_b32 s42, s42, s30
	s_lshr_b32 s0, s42, 8
	s_and_b32 s1, s42, 255
	s_and_b32 s42, s1, 15
	s_lshr_b32 s1, s1, 4
	s_mul_i32 s9, s0, 0x400000
	s_mul_i32 s10, s42, 0x40000
	s_add_u32 s9, s9, s10
	s_lshl_b32 s10, s1, 8
	s_add_u32 s9, s9, s10
	s_add_u32 s62, s6, s9
	s_addc_u32 s63, s7, 0
	s_add_u32 s64, s62, 0x20000
	s_addc_u32 s65, s63, 0
	v_lshl_add_u32 v122, v112, 2, v80
	global_load_dwordx4 v[72:75], v122, s[62:63]
	global_load_dwordx4 v[76:79], v122, s[64:65]
	s_waitcnt lgkmcnt(0)
	s_barrier
	ds_read_b32 v113, v82 offset:16640
	ds_read_b32 v114, v82 offset:16900
	ds_read_b32 v115, v82 offset:17160
	ds_read_b32 v116, v82 offset:17420
	ds_read_b32 v117, v82 offset:17680
	ds_read_b32 v118, v82 offset:17940
	ds_read_b32 v119, v82 offset:18200
	ds_read_b32 v120, v82 offset:18460
	s_mul_i32 s9, s11, 0x200000
	s_mul_i32 s10, s31, 0x20000
	s_add_u32 s9, s9, s10
	s_lshl_b32 s10, s32, 7
	s_add_u32 s9, s9, s10
	s_add_u32 s66, s20, s9
	s_addc_u32 s67, s21, 0
	s_waitcnt lgkmcnt(0)
	v_cvt_pk_bf16_f32 v128, v113, v114
	v_cvt_pk_bf16_f32 v129, v115, v116
	v_cvt_pk_bf16_f32 v130, v117, v118
	v_cvt_pk_bf16_f32 v131, v119, v120
	global_store_dwordx4 v83, v[128:131], s[66:67]
	s_addk_i32 s30, 0x100
	s_cmpk_lt_u32 s30, 0x400
	s_cbranch_scc1 .Lpre_wout_loop
	s_waitcnt vmcnt(0)
	s_barrier
	s_branch .LBB0_9

; DEV void pre_item(const Params& p, int it, char* smem, int tid) {
;   if (it < PRE_MOD) { mod_item(p, it, smem, tid); return; }
;   it -= PRE_MOD;
;   if (it < 1) { misc_item(p, tid); return; }
;   it -= 1;
;   if (it < PRE_T_IN) {
;     int l = it / 2176, r = it % 2176;
;     transpose_item(p.w_in + (long)l * 1024 * NIN, NIN, 1024, p.WinT + (long)l * NINP * 1024, nullptr, r / 16, r % 16, smem, tid);
;     return;
;   }
;   it -= PRE_T_IN;
;   if (it < PRE_T_UQ) {
;     int l = it / 48, r = it % 48;
;     transpose_item(p.w_uq + (long)l * 256 * 768, 768, 256, p.WuqT + (long)l * 768 * 256, p.q_norm_g + l * 256, r / 4, r % 4, smem, tid);
;     return;
;   }
;   it -= PRE_T_UQ;
;   if (it < PRE_T_UKV) {
;     int l = it / 32, r = it % 32;
;     transpose_item(p.w_ukv + (long)l * 128 * 1024, 1024, 128, p.WukvT + (long)l * 1024 * 128, p.kv_norm_g + l * 128, r / 2, r % 2, smem, tid);
;     return;
;   }
;   it -= PRE_T_UKV;
;   if (it < PRE_T_BR) {
;     int m = it / 128, r = it % 128;
;     transpose_item(p.w_branch + (long)m * 512 * 1024, 1024, 512, p.WbrT + (long)m * 1024 * 512, nullptr, r / 8, r % 8, smem, tid);
;     return;
;   }
;   it -= PRE_T_BR;
;   {
;     int l = it / 256, r = it % 256;
;     transpose_item(p.w_out + (long)l * 1024 * 1024, 1024, 1024, p.WoutT + (long)l * 1024 * 1024, nullptr, r / 16, r % 16, smem, tid);
;   }
.LBB0_9:
	v_mov_b32_e32 v12, v197
	s_cmpk_gt_i32 s97, 0xbf
	s_mov_b64 s[4:5], -1
	s_cbranch_scc0 .LBB0_56
	s_cmpk_lg_i32 s97, 0xc0
	s_cbranch_scc0 .LBB0_40
	s_cmpk_gt_u32 s97, 0x22c0
	s_mov_b64 s[10:11], -1
	s_cbranch_scc0 .LBB0_8
	s_cmpk_gt_u32 s97, 0x2380
	s_cbranch_scc0 .LBB0_26
	s_cmpk_gt_u32 s97, 0x2400
	s_cbranch_scc0 .LBB0_19
	s_branch .LBB0_8
	s_cmpk_gt_u32 s97, 0x2a00
	s_mov_b64 s[8:9], -1
	s_cbranch_scc0 .LBB0_16
	s_add_i32 s7, s97, 0xffffd5ff
	s_lshr_b32 s42, s7, 8
	v_readlane_b32 s8, v253, 7
	s_lshl_b64 s[4:5], s[42:43], 22
	v_readlane_b32 s10, v253, 9
	v_readlane_b32 s9, v253, 8
	v_readlane_b32 s11, v253, 10
	s_add_u32 s8, s10, s4
	s_addc_u32 s9, s11, s5
	s_lshl_b64 s[4:5], s[42:43], 21
	s_add_u32 s4, s20, s4
	s_addc_u32 s5, s21, s5
	v_lshlrev_b32_e32 v2, 2, v12
	s_lshl_b32 s6, s7, 6
	s_lshl_b32 s7, s7, 2
	v_ashrrev_i32_e32 v13, 4, v12
	v_and_b32_e32 v14, 60, v2
	s_and_b32 s6, s6, 0x3c0
	s_and_b32 s7, s7, 0x3c0
	v_or_b32_e32 v2, s7, v14
	v_add_u32_e32 v8, s6, v13
	v_lshlrev_b32_e32 v10, 2, v2
	v_ashrrev_i32_e32 v9, 31, v8
	v_lshl_add_u64 v[6:7], s[8:9], 0, v[10:11]
	v_lshlrev_b64 v[2:3], 12, v[8:9]
	v_add_u32_e32 v8, 32, v8
	v_lshl_add_u64 v[2:3], v[6:7], 0, v[2:3]
	v_ashrrev_i32_e32 v9, 31, v8
	s_barrier
	global_load_dwordx4 v[2:5], v[2:3], off
	v_lshlrev_b64 v[8:9], 12, v[8:9]
	v_lshl_add_u64 v[6:7], v[6:7], 0, v[8:9]
	global_load_dwordx4 v[6:9], v[6:7], off
	v_mul_lo_u32 v10, v13, s68
	v_lshl_add_u32 v10, v14, 2, v10
	v_add_u32_e32 v13, 0x2080, v10
	v_add_u32_e32 v14, 0x2088, v10
	s_mov_b64 s[8:9], 0
	s_waitcnt vmcnt(1)
	ds_write2_b32 v10, v2, v3 offset1:1
	ds_write2_b32 v10, v4, v5 offset0:2 offset1:3
	s_waitcnt vmcnt(0)
	ds_write2_b32 v13, v6, v7 offset1:1
	ds_write2_b32 v14, v8, v9 offset1:1
	s_waitcnt lgkmcnt(0)
	s_barrier
